# scan loop: gain loads hoisted, mid-step vmcnt waits removed
# baseline (speedup 1.0000x reference)
.LBB0_443:
	s_and_b32 s6, s34, 0xff
	s_mulk_i32 s6, 0xab
	s_lshr_b32 s44, s6, 11
	s_mul_i32 s6, s44, 12
	s_lshl_b32 s30, s34, 6
	s_sub_i32 s35, s34, s6
	s_lshl_b64 s[36:37], s[30:31], 13
	v_readlane_b32 s7, v252, 23
	s_mov_b32 s6, 0
	s_add_u32 s16, s7, s6
	v_readlane_b32 s7, v252, 24
	s_addc_u32 s17, s7, 0
	s_ashr_i32 s9, s6, 31
	s_mov_b32 s8, s6
	s_lshl_b64 s[8:9], s[8:9], 3
	v_readlane_b32 s46, v252, 3
	v_readlane_b32 s47, v252, 4
	s_add_u32 s8, s46, s8
	s_addc_u32 s9, s47, s9
	v_readlane_b32 s7, v253, 45
	s_add_u32 s22, s7, s6
	v_readlane_b32 s7, v253, 46
	s_addc_u32 s23, s7, 0
	v_readlane_b32 s7, v253, 47
	s_add_u32 s24, s7, s6
	v_readlane_b32 s7, v253, 48
	s_addc_u32 s25, s7, 0
	v_readlane_b32 s7, v253, 49
	s_add_u32 s26, s7, s6
	v_readlane_b32 s7, v253, 50
	v_mov_b32 v118, v0
	s_load_dwordx2 s[8:9], s[8:9], 0x48
	s_addc_u32 s27, s7, 0
	s_add_u32 s28, s87, s6
	s_addc_u32 s29, s88, 0
	s_add_u32 s12, s89, s6
	s_addc_u32 s13, s90, 0
	s_waitcnt lgkmcnt(0)
	s_add_u32 s8, s8, s2
	s_addc_u32 s9, s9, s3
	s_lshl_b64 s[40:41], s[30:31], 14
	v_add_u32_e32 v46, 0x200, v118
	s_add_u32 s42, s22, s40
	v_ashrrev_i32_e32 v119, 31, v118
	v_ashrrev_i32_e32 v47, 31, v46
	s_addc_u32 s43, s23, s41
	v_lshlrev_b64 v[120:121], 4, v[118:119]
	v_lshlrev_b64 v[122:123], 4, v[46:47]
	v_lshl_add_u64 v[2:3], s[42:43], 0, v[120:121]
	v_lshl_add_u64 v[6:7], s[42:43], 0, v[122:123]
	s_add_u32 s42, s28, s40
	s_addc_u32 s43, s29, s41
	s_add_u32 s36, s12, s36
	s_addc_u32 s37, s13, s37
	s_waitcnt vmcnt(6)
	v_lshl_add_u64 v[18:19], s[36:37], 0, v[120:121]
	s_add_u32 s36, s24, s40
	s_addc_u32 s37, s25, s41
	v_lshl_add_u64 v[22:23], s[36:37], 0, v[120:121]
	s_waitcnt vmcnt(5)
	v_lshl_add_u64 v[26:27], s[36:37], 0, v[122:123]
	s_lshl_b64 s[36:37], s[30:31], 15
	v_add_u32_e32 v48, 0x400, v118
	v_add_u32_e32 v50, 0x600, v118
	s_add_u32 s36, s26, s36
	v_ashrrev_i32_e32 v49, 31, v48
	v_ashrrev_i32_e32 v51, 31, v50
	s_addc_u32 s37, s27, s37
	v_lshlrev_b64 v[124:125], 4, v[48:49]
	v_lshlrev_b64 v[126:127], 4, v[50:51]
	v_lshl_add_u64 v[10:11], s[42:43], 0, v[120:121]
	v_lshl_add_u64 v[14:15], s[42:43], 0, v[122:123]
	s_waitcnt vmcnt(4)
	v_lshl_add_u64 v[30:31], s[36:37], 0, v[120:121]
	v_lshl_add_u64 v[34:35], s[36:37], 0, v[122:123]
	v_lshl_add_u64 v[38:39], s[36:37], 0, v[124:125]
	v_lshl_add_u64 v[42:43], s[36:37], 0, v[126:127]
	global_load_dwordx4 v[2:5], v[2:3], off
	s_nop 0
	global_load_dwordx4 v[6:9], v[6:7], off
	s_nop 0
	global_load_dwordx4 v[10:13], v[10:11], off
	s_nop 0
	global_load_dwordx4 v[14:17], v[14:15], off
	s_nop 0
	global_load_dwordx4 v[18:21], v[18:19], off
	s_nop 0
	global_load_dwordx4 v[22:25], v[22:23], off
	s_nop 0
	global_load_dwordx4 v[26:29], v[26:27], off
	v_lshlrev_b32_e32 v51, 4, v118
	global_load_dwordx4 v[30:33], v[30:31], off
	v_and_b32_e32 v53, 0xf0, v51
	global_load_dwordx4 v[34:37], v[34:35], off
	v_lshrrev_b32_e32 v58, 4, v46
	global_load_dwordx4 v[38:41], v[38:39], off
	v_lshrrev_b32_e32 v65, 3, v46
	global_load_dwordx4 v[42:45], v[42:43], off
	v_and_b32_e32 v51, 0x1f0, v51
	v_lshlrev_b64 v[56:57], 3, v[46:47]
	v_readlane_b32 s43, v255, 17
	v_ashrrev_i32_e32 v46, 5, v46
	v_mul_lo_u32 v46, v46, s93
	v_add_u32_e32 v51, s43, v51
	v_lshrrev_b32_e32 v49, 4, v118
	v_add_u32_e32 v159, v51, v46
	v_ashrrev_i32_e32 v46, 5, v48
	v_ashrrev_i32_e32 v62, 3, v118
	v_mul_lo_u32 v49, v49, s94
	s_movk_i32 s34, 0x90
	v_mul_lo_u32 v46, v46, s93
	v_ashrrev_i32_e32 v52, 5, v118
	v_lshlrev_b64 v[54:55], 3, v[118:119]
	v_mul_lo_u32 v59, v62, s34
	v_add3_u32 v119, 0, v49, v53
	v_mul_lo_u32 v47, v58, s94
	v_mul_lo_u32 v49, v65, s34
	v_readlane_b32 s34, v253, 51
	v_add_u32_e32 v160, v51, v46
	v_ashrrev_i32_e32 v46, 5, v50
	v_add3_u32 v156, 0, v47, v53
	s_add_u32 s34, s34, s6
	v_readlane_b32 s36, v253, 52
	v_mul_lo_u32 v47, v52, s93
	v_mul_lo_u32 v46, v46, s93
	s_addc_u32 s41, s36, 0
	s_lshl_b64 s[36:37], s[30:31], 2
	v_add_u32_e32 v158, v51, v47
	v_add_u32_e32 v161, v51, v46
	v_lshl_add_u32 v58, s44, 12, v62
	v_mov_b64_e32 v[46:47], s[16:17]
	s_add_u32 s40, s34, s36
	v_mad_i64_i32 v[46:47], s[16:17], v58, s15, v[46:47]
	s_addc_u32 s41, s41, s37
	s_and_b32 s16, s35, 0xff
	v_and_b32_e32 v63, 7, v118
	s_lshl_b32 s34, s16, 8
	s_mov_b32 s35, s31
	v_lshl_add_u64 v[46:47], v[46:47], 0, s[34:35]
	v_lshlrev_b32_e32 v130, 5, v63
	v_lshl_add_u64 v[46:47], v[46:47], 0, v[130:131]
	s_mov_b64 s[16:17], 0x5000
	v_lshl_add_u64 v[50:51], v[46:47], 0, s[16:17]
	s_movk_i32 s17, 0x5000
	v_lshlrev_b32_e32 v64, 4, v63
	v_add_co_u32_e32 v46, vcc, s17, v46
	v_add3_u32 v143, 0, v59, v64
	v_add3_u32 v157, 0, v49, v64
	global_load_dword v162, v131, s[40:41]
	s_waitcnt vmcnt(11)
	ds_write_b128 v119, v[2:5]
	s_waitcnt vmcnt(10)
	ds_write_b128 v156, v[6:9]
	s_waitcnt vmcnt(9)
	ds_write_b128 v119, v[10:13] offset:17408
	s_waitcnt vmcnt(8)
	ds_write_b128 v156, v[14:17] offset:17408
	s_waitcnt vmcnt(7)
	ds_write_b128 v143, v[18:21] offset:34816
	s_waitcnt vmcnt(6)
	ds_write_b128 v143, v[22:25] offset:44032
	s_waitcnt vmcnt(5)
	ds_write_b128 v157, v[26:29] offset:44032
	v_addc_co_u32_e32 v47, vcc, 0, v47, vcc
	s_waitcnt vmcnt(4)
	ds_write_b128 v158, v[30:33]
	s_waitcnt vmcnt(3)
	ds_write_b128 v159, v[34:37]
	v_and_b32_e32 v60, 15, v118
	s_waitcnt vmcnt(2)
	ds_write_b128 v160, v[38:41]
	v_bfe_u32 v61, v118, 4, 2
	s_waitcnt vmcnt(1)
	ds_write_b128 v161, v[42:45]
	global_load_dwordx4 v[46:49], v[46:47], off
	s_nop 0
	global_load_dwordx4 v[50:53], v[50:51], off offset:16
	v_mul_u32_u24_e32 v66, 0x88, v60
	v_mul_u32_u24_e32 v64, 0x840, v61
	v_lshlrev_b32_e32 v66, 1, v66
	v_lshlrev_b32_e32 v61, 4, v61
	v_readfirstlane_b32 s42, v118
	v_lshlrev_b32_e32 v65, 2, v60
	v_add3_u32 v164, 0, v66, v61
	v_lshlrev_b32_e32 v60, 7, v60
	s_and_b32 s17, s42, 0xffffffc0
	v_sub_u32_e32 v165, v164, v60
	v_lshlrev_b32_e32 v60, 6, v63
	v_mov_b32_e32 v61, v131
	s_add_i32 s40, s17, s43
	v_lshl_add_u64 v[128:129], s[12:13], 0, v[120:121]
	s_add_i32 s12, s17, 0
	v_lshl_add_u64 v[132:133], s[8:9], 0, v[60:61]
	v_readlane_b32 s8, v255, 7
	v_add3_u32 v166, s12, v65, v64
	s_add_u32 s12, s8, s36
	v_readlane_b32 s8, v255, 8
	s_addc_u32 s13, s8, s37
	s_load_dwordx2 s[36:37], s[46:47], 0x88
	v_ashrrev_i32_e32 v59, 31, v58
	v_add_u32_e32 v63, 0, v60
	v_lshlrev_b64 v[60:61], 13, v[58:59]
	v_lshl_add_u64 v[60:61], v[60:61], 0, s[34:35]
	v_or_b32_e32 v60, v60, v130
	s_waitcnt lgkmcnt(0)
	v_lshl_add_u64 v[134:135], s[36:37], 0, v[60:61]
	v_mov_b64_e32 v[60:61], s[34:35]
	s_waitcnt lgkmcnt(0)
	s_barrier
	v_mad_i64_i32 v[58:59], s[8:9], v58, s15, v[60:61]
	v_mul_lo_u32 v66, v62, s93
	v_or_b32_e32 v58, v58, v130
	v_mov_b32_e32 v94, 0
	v_mov_b32_e32 v62, 0
	s_mov_b32 s7, s31
	s_mov_b32 s16, 0
	v_add3_u32 v163, s40, v64, v65
	v_add_u32_e32 v167, 0xf400, v166
	v_lshl_add_u64 v[136:137], s[36:37], 0, v[58:59]
	s_or_b32 s17, s30, 1
	v_lshlrev_b64 v[138:139], 1, v[54:55]
	v_lshlrev_b64 v[140:141], 1, v[56:57]
	v_add_u32_e32 v168, v63, v66
	v_mov_b32_e32 v63, v62
	v_mov_b32_e32 v64, v62
	v_mov_b32_e32 v65, v62
	v_mov_b32_e32 v66, v62
	v_mov_b32_e32 v67, v62
	v_mov_b32_e32 v68, v62
	s_waitcnt vmcnt(2)
	v_mov_b32_e32 v130, v162
	v_mov_b32_e32 v69, v62
	v_mov_b32_e32 v74, v62
	v_mov_b32_e32 v75, v62
	v_mov_b32_e32 v76, v62
	v_mov_b32_e32 v77, v62
	v_mov_b32_e32 v70, v62
	v_mov_b32_e32 v71, v62
	v_mov_b32_e32 v72, v62
	v_mov_b32_e32 v73, v62
	v_mov_b32_e32 v78, v62
	v_mov_b32_e32 v79, v62
	v_mov_b32_e32 v80, v62
	v_mov_b32_e32 v81, v62
	v_mov_b32_e32 v82, v62
	v_mov_b32_e32 v83, v62
	v_mov_b32_e32 v84, v62
	v_mov_b32_e32 v85, v62
	v_mov_b32_e32 v86, v62
	v_mov_b32_e32 v87, v62
	v_mov_b32_e32 v88, v62
	v_mov_b32_e32 v89, v62
	v_mov_b32_e32 v90, v62
	v_mov_b32_e32 v91, v62
	v_mov_b32_e32 v92, v62
	v_mov_b32_e32 v93, v62
	v_mov_b32_e32 v95, v94
	v_mov_b32_e32 v96, v94
	v_mov_b32_e32 v97, v94
	v_mov_b32_e32 v98, v94
	v_mov_b32_e32 v99, v94
	v_mov_b32_e32 v100, v94
	v_mov_b32_e32 v101, v94
	v_mov_b32_e32 v102, v94
	v_mov_b32_e32 v103, v94
	v_mov_b32_e32 v104, v94
	v_mov_b32_e32 v105, v94
	v_mov_b32_e32 v106, v94
	v_mov_b32_e32 v107, v94
	v_mov_b32_e32 v108, v94
	v_mov_b32_e32 v109, v94
	global_load_dwordx4 v[242:245], v[132:133], off
	global_load_dwordx4 v[246:249], v[132:133], off offset:16
	global_load_dwordx2 v[250:251], v[132:133], off offset:32
	global_load_dword v241, v[132:133], off offset:40
	global_load_dword v228, v[132:133], off offset:44
	global_load_dword v230, v[132:133], off offset:48
	global_load_dword v234, v[132:133], off offset:52
	global_load_dword v236, v[132:133], off offset:56
	global_load_dword v238, v[132:133], off offset:60
	s_waitcnt vmcnt(0)
	s_branch .LBB0_445

.LBB0_447:
	ds_read_b128 v[110:113], v164 offset:17408
	ds_read_b128 v[114:117], v164 offset:17472
	ds_read_b128 v[144:147], v164 offset:17536
	ds_read_b128 v[148:151], v164 offset:17600
	ds_read_b128 v[152:155], v164 offset:21760
	ds_read_b128 v[170:173], v164 offset:21824
	ds_read_b128 v[174:177], v164 offset:21888
	ds_read_b128 v[178:181], v164 offset:21952
	s_waitcnt lgkmcnt(7)
	v_mfma_f32_16x16x32_bf16 v[110:113], v[110:113], v[94:97], 0
	s_waitcnt lgkmcnt(6)
	v_mfma_f32_16x16x32_bf16 v[110:113], v[114:117], v[98:101], v[110:113]
	s_waitcnt lgkmcnt(5)
	v_mfma_f32_16x16x32_bf16 v[110:113], v[144:147], v[102:105], v[110:113]
	s_waitcnt lgkmcnt(4)
	v_mfma_f32_16x16x32_bf16 v[110:113], v[148:151], v[106:109], v[110:113]
	ds_read_b128 v[114:117], v164 offset:26112
	ds_read_b128 v[144:147], v164 offset:26176
	ds_read_b128 v[148:151], v164 offset:26240
	ds_read_b128 v[182:185], v164 offset:26304
	s_waitcnt lgkmcnt(7)
	v_mfma_f32_16x16x32_bf16 v[152:155], v[152:155], v[94:97], 0
	s_waitcnt lgkmcnt(6)
	v_mfma_f32_16x16x32_bf16 v[152:155], v[170:173], v[98:101], v[152:155]
	s_waitcnt lgkmcnt(5)
	v_mfma_f32_16x16x32_bf16 v[152:155], v[174:177], v[102:105], v[152:155]
	s_waitcnt lgkmcnt(4)
	v_mfma_f32_16x16x32_bf16 v[152:155], v[178:181], v[106:109], v[152:155]
	ds_read_b128 v[170:173], v164 offset:30464
	ds_read_b128 v[174:177], v164 offset:30528
	ds_read_b128 v[178:181], v164 offset:30592
	ds_read_b128 v[186:189], v164 offset:30656
	s_waitcnt lgkmcnt(7)
	v_mfma_f32_16x16x32_bf16 v[114:117], v[114:117], v[94:97], 0
	s_waitcnt lgkmcnt(6)
	v_mfma_f32_16x16x32_bf16 v[114:117], v[144:147], v[98:101], v[114:117]
	s_waitcnt lgkmcnt(5)
	v_mfma_f32_16x16x32_bf16 v[114:117], v[148:151], v[102:105], v[114:117]
	s_waitcnt lgkmcnt(4)
	v_mfma_f32_16x16x32_bf16 v[114:117], v[182:185], v[106:109], v[114:117]
	ds_read_b128 v[144:147], v164
	ds_read_b128 v[148:151], v164 offset:64
	ds_read_b128 v[182:185], v164 offset:128
	ds_read_b128 v[190:193], v164 offset:192
	s_waitcnt lgkmcnt(7)
	v_mfma_f32_16x16x32_bf16 v[170:173], v[170:173], v[94:97], 0
	s_waitcnt lgkmcnt(6)
	v_mfma_f32_16x16x32_bf16 v[170:173], v[174:177], v[98:101], v[170:173]
	s_waitcnt lgkmcnt(5)
	v_mfma_f32_16x16x32_bf16 v[170:173], v[178:181], v[102:105], v[170:173]
	s_waitcnt lgkmcnt(4)
	v_mfma_f32_16x16x32_bf16 v[170:173], v[186:189], v[106:109], v[170:173]
	ds_read_b128 v[174:177], v164 offset:4352
	ds_read_b128 v[178:181], v164 offset:4416
	ds_read_b128 v[186:189], v164 offset:4480
	ds_read_b128 v[194:197], v164 offset:4544
	v_add_u32_e32 v142, 0x400, v163
	ds_read2_b32 v[198:199], v163 offset1:132
	ds_read2_b32 v[200:201], v142 offset0:8 offset1:140
	s_waitcnt lgkmcnt(0)
	v_mfma_f32_16x16x32_bf16 v[144:147], v[144:147], v[94:97], v[198:201]
	v_mfma_f32_16x16x32_bf16 v[144:147], v[148:151], v[98:101], v[144:147]
	v_mfma_f32_16x16x32_bf16 v[144:147], v[182:185], v[102:105], v[144:147]
	v_mfma_f32_16x16x32_bf16 v[144:147], v[190:193], v[106:109], v[144:147]
	ds_read_b128 v[148:151], v164 offset:8704
	ds_read_b128 v[182:185], v164 offset:8768
	ds_read_b128 v[190:193], v164 offset:8832
	ds_read_b128 v[198:201], v164 offset:8896
	v_add_u32_e32 v142, 0x2000, v163
	ds_read2_b32 v[202:203], v142 offset0:64 offset1:196
	v_add_u32_e32 v142, 0x2400, v163
	ds_read2_b32 v[204:205], v142 offset0:72 offset1:204
	s_waitcnt lgkmcnt(0)
	v_mfma_f32_16x16x32_bf16 v[174:177], v[174:177], v[94:97], v[202:205]
	v_mfma_f32_16x16x32_bf16 v[174:177], v[178:181], v[98:101], v[174:177]
	v_mfma_f32_16x16x32_bf16 v[174:177], v[186:189], v[102:105], v[174:177]
	v_mfma_f32_16x16x32_bf16 v[174:177], v[194:197], v[106:109], v[174:177]
	ds_read_b128 v[178:181], v164 offset:13056
	ds_read_b128 v[186:189], v164 offset:13120
	ds_read_b128 v[194:197], v164 offset:13184
	ds_read_b128 v[202:205], v164 offset:13248
	v_add_u32_e32 v142, 0x4200, v163
	ds_read2_b32 v[206:207], v142 offset1:132
	v_add_u32_e32 v142, 0x4600, v163
	ds_read2_b32 v[208:209], v142 offset0:8 offset1:140
	s_waitcnt lgkmcnt(0)
	v_mfma_f32_16x16x32_bf16 v[148:151], v[148:151], v[94:97], v[206:209]
	v_mfma_f32_16x16x32_bf16 v[148:151], v[182:185], v[98:101], v[148:151]
	v_mfma_f32_16x16x32_bf16 v[148:151], v[190:193], v[102:105], v[148:151]
	v_mfma_f32_16x16x32_bf16 v[148:151], v[198:201], v[106:109], v[148:151]
	ds_read_b128 v[182:185], v165 offset:34816
	ds_read_b128 v[190:193], v165 offset:34880
	ds_read_b128 v[198:201], v165 offset:37120
	ds_read_b128 v[206:209], v165 offset:37184
	v_add_u32_e32 v142, 0x6200, v163
	ds_read2_b32 v[210:211], v142 offset0:64 offset1:196
	v_add_u32_e32 v142, 0x6600, v163
	ds_read2_b32 v[212:213], v142 offset0:72 offset1:204
	s_waitcnt lgkmcnt(0)
	v_mfma_f32_16x16x32_bf16 v[94:97], v[178:181], v[94:97], v[210:213]
	v_mfma_f32_16x16x32_bf16 v[94:97], v[186:189], v[98:101], v[94:97]
	v_mfma_f32_16x16x32_bf16 v[94:97], v[194:197], v[102:105], v[94:97]
	ds_read_b128 v[98:101], v165 offset:39424
	ds_read_b128 v[102:105], v165 offset:39488
	ds_read_b128 v[178:181], v165 offset:41728
	ds_read_b128 v[186:189], v165 offset:41792
	v_mfma_f32_16x16x32_bf16 v[94:97], v[202:205], v[106:109], v[94:97]
	v_cvt_pk_bf16_f32 v106, v144, v145
	v_cvt_pk_bf16_f32 v107, v146, v147
	v_cvt_pk_bf16_f32 v108, v174, v175
	v_cvt_pk_bf16_f32 v109, v176, v177
	v_cvt_pk_bf16_f32 v144, v148, v149
	v_cvt_pk_bf16_f32 v145, v150, v151
	v_mfma_f32_16x16x32_bf16 v[110:113], v[182:185], v[106:109], v[110:113]
	s_nop 0
	v_cvt_pk_bf16_f32 v146, v94, v95
	v_cvt_pk_bf16_f32 v147, v96, v97
	s_nop 1
	v_mfma_f32_16x16x32_bf16 v[94:97], v[190:193], v[144:147], v[110:113]
	v_mfma_f32_16x16x32_bf16 v[110:113], v[198:201], v[106:109], v[152:155]
	ds_read_b128 v[148:151], v165 offset:44032
	s_nop 1
	ds_read_b128 v[152:155], v165 offset:44096
	ds_read_b128 v[174:177], v165 offset:46336
	ds_read_b128 v[182:185], v165 offset:46400
	v_mfma_f32_16x16x32_bf16 v[110:113], v[206:209], v[144:147], v[110:113]
	s_waitcnt lgkmcnt(7)
	v_mfma_f32_16x16x32_bf16 v[98:101], v[98:101], v[106:109], v[114:117]
	s_waitcnt lgkmcnt(6)
	v_mfma_f32_16x16x32_bf16 v[98:101], v[102:105], v[144:147], v[98:101]
	s_waitcnt lgkmcnt(5)
	v_mfma_f32_16x16x32_bf16 v[102:105], v[178:181], v[106:109], v[170:173]
	s_waitcnt lgkmcnt(4)
	v_mfma_f32_16x16x32_bf16 v[102:105], v[186:189], v[144:147], v[102:105]
	ds_read_b128 v[114:117], v165 offset:48640
	ds_read_b128 v[170:173], v165 offset:48704
	ds_read_b128 v[178:181], v165 offset:50944
	ds_read_b128 v[186:189], v165 offset:51008
	v_pk_mul_f32 v[64:65], v[64:65], v[130:131] op_sel_hi:[1,0]
	v_pk_mul_f32 v[62:63], v[62:63], v[130:131] op_sel_hi:[1,0]
	v_pk_mul_f32 v[68:69], v[68:69], v[130:131] op_sel_hi:[1,0]
	v_pk_mul_f32 v[66:67], v[66:67], v[130:131] op_sel_hi:[1,0]
	s_waitcnt lgkmcnt(7)
	v_mfma_f32_16x16x32_bf16 v[62:65], v[148:151], v[106:109], v[62:65]
	v_mul_f32_e64 v76, v76, v130
	v_mul_f32_e64 v77, v77, v130
	v_pk_mul_f32 v[74:75], v[74:75], v[130:131] op_sel_hi:[1,0]
	v_pk_mul_f32 v[72:73], v[72:73], v[130:131] op_sel_hi:[1,0]
	s_waitcnt lgkmcnt(5)
	v_mfma_f32_16x16x32_bf16 v[66:69], v[174:177], v[106:109], v[66:69]
	v_mul_f32_e64 v70, v70, v130
	v_mul_f32_e64 v71, v71, v130
	v_pk_mul_f32 v[80:81], v[80:81], v[130:131] op_sel_hi:[1,0]
	v_pk_mul_f32 v[78:79], v[78:79], v[130:131] op_sel_hi:[1,0]
	v_mfma_f32_16x16x32_bf16 v[62:65], v[152:155], v[144:147], v[62:65]
	v_mul_f32_e64 v84, v84, v130
	v_mul_f32_e64 v85, v85, v130
	v_pk_mul_f32 v[82:83], v[82:83], v[130:131] op_sel_hi:[1,0]
	v_pk_mul_f32 v[88:89], v[88:89], v[130:131] op_sel_hi:[1,0]
	s_waitcnt lgkmcnt(4)
	v_mfma_f32_16x16x32_bf16 v[66:69], v[182:185], v[144:147], v[66:69]
	ds_read_b128 v[148:151], v165 offset:53248
	ds_read_b128 v[152:155], v165 offset:53312
	ds_read_b128 v[174:177], v165 offset:55552
	ds_read_b128 v[182:185], v165 offset:55616
	v_pk_mul_f32 v[86:87], v[86:87], v[130:131] op_sel_hi:[1,0]
	v_pk_mul_f32 v[92:93], v[92:93], v[130:131] op_sel_hi:[1,0]
	v_pk_mul_f32 v[90:91], v[90:91], v[130:131] op_sel_hi:[1,0]
	s_waitcnt lgkmcnt(7)
	v_mfma_f32_16x16x32_bf16 v[74:77], v[114:117], v[106:109], v[74:77]
	s_waitcnt lgkmcnt(5)
	v_mfma_f32_16x16x32_bf16 v[70:73], v[178:181], v[106:109], v[70:73]
	v_mfma_f32_16x16x32_bf16 v[74:77], v[170:173], v[144:147], v[74:77]
	s_waitcnt lgkmcnt(4)
	v_mfma_f32_16x16x32_bf16 v[70:73], v[186:189], v[144:147], v[70:73]
	ds_read_b128 v[114:117], v165 offset:57856
	ds_read_b128 v[170:173], v165 offset:57920
	ds_read_b128 v[178:181], v165 offset:60160
	ds_read_b128 v[186:189], v165 offset:60224
	s_waitcnt lgkmcnt(7)
	v_mfma_f32_16x16x32_bf16 v[78:81], v[148:151], v[106:109], v[78:81]
	s_waitcnt lgkmcnt(5)
	v_mfma_f32_16x16x32_bf16 v[82:85], v[174:177], v[106:109], v[82:85]
	v_mfma_f32_16x16x32_bf16 v[78:81], v[152:155], v[144:147], v[78:81]
	s_waitcnt lgkmcnt(4)
	v_mfma_f32_16x16x32_bf16 v[82:85], v[182:185], v[144:147], v[82:85]
	ds_write2_b32 v167, v94, v95 offset1:132
	v_add_u32_e32 v94, 0xf800, v166
	ds_write2_b32 v94, v96, v97 offset0:8 offset1:140
	v_add_u32_e32 v94, 0x2000, v167
	ds_write2_b32 v94, v110, v111 offset0:64 offset1:196
	v_add_u32_e32 v94, 0x2400, v167
	ds_write2_b32 v94, v112, v113 offset0:72 offset1:204
	v_add_u32_e32 v94, 0x4200, v167
	ds_write2_b32 v94, v98, v99 offset1:132
	v_add_u32_e32 v94, 0x4600, v167
	ds_write2_b32 v94, v100, v101 offset0:8 offset1:140
	v_add_u32_e32 v94, 0x6200, v167
	ds_write2_b32 v94, v102, v103 offset0:64 offset1:196
	v_add_u32_e32 v94, 0x6600, v167
	ds_write2_b32 v94, v104, v105 offset0:72 offset1:204
	s_waitcnt lgkmcnt(0)
	s_barrier
	ds_read_b128 v[110:113], v168 offset:62464
	ds_read_b128 v[102:105], v168 offset:62480
	ds_read_b128 v[98:101], v168 offset:62496
	ds_read_b128 v[94:97], v168 offset:62512
	s_waitcnt lgkmcnt(14)
	v_mfma_f32_16x16x32_bf16 v[86:89], v[114:117], v[106:109], v[86:89]
	v_lshlrev_b32_e32 v150, 16, v46
	v_lshlrev_b32_e32 v151, 16, v47
	s_mov_b32 s30, 0x5f901000
	s_waitcnt lgkmcnt(13)
	v_mfma_f32_16x16x32_bf16 v[90:93], v[178:181], v[106:109], v[90:93]
	s_waitcnt lgkmcnt(3)
	v_pk_mul_f32 v[106:107], v[112:113], v[112:113]
	v_pk_mul_f32 v[108:109], v[110:111], v[110:111]
	s_nop 0
	v_pk_mov_b32 v[114:115], v[108:109], v[106:107] op_sel:[1,0]
	v_mov_b32_e32 v109, v107
	v_pk_add_f32 v[106:107], v[114:115], v[108:109]
	s_waitcnt lgkmcnt(2)
	v_pk_mul_f32 v[108:109], v[104:105], v[104:105]
	v_pk_mul_f32 v[114:115], v[102:103], v[102:103]
	v_pk_add_f32 v[106:107], v[106:107], v[106:107] op_sel:[0,1] op_sel_hi:[1,0]
	v_pk_mov_b32 v[116:117], v[114:115], v[108:109] op_sel:[1,0]
	v_mov_b32_e32 v115, v109
	v_pk_add_f32 v[108:109], v[116:117], v[114:115]
	s_waitcnt lgkmcnt(0)
	v_mul_f32_e32 v114, v94, v94
	v_mul_f32_e32 v115, v95, v95
	v_pk_add_f32 v[108:109], v[108:109], v[108:109] op_sel:[0,1] op_sel_hi:[1,0]
	v_mov_b32_e32 v107, v114
	v_mov_b32_e32 v109, v115
	v_pk_add_f32 v[106:107], v[106:107], v[108:109]
	v_mul_f32_e32 v108, v99, v99
	v_mul_f32_e32 v114, v101, v101
	v_mul_f32_e32 v116, v96, v96
	v_mul_f32_e32 v117, v97, v97
	v_pk_fma_f32 v[108:109], v[98:99], v[98:99], v[108:109] op_sel_hi:[1,1,0]
	v_pk_fma_f32 v[114:115], v[100:101], v[100:101], v[114:115] op_sel_hi:[1,1,0]
	v_mov_b32_e32 v109, v116
	v_mov_b32_e32 v115, v117
	v_pk_add_f32 v[108:109], v[108:109], v[114:115]
	v_mfma_f32_16x16x32_bf16 v[86:89], v[170:173], v[144:147], v[86:89]
	v_add_f32_e64 v106, v106, v108
	v_add_f32_e64 v107, v107, v109
	v_and_b32_e32 v108, 64, v235
	v_add_f32_e32 v106, v106, v107
	v_xor_b32_e32 v107, 1, v235
	v_add_u32_e32 v108, 64, v108
	v_cmp_lt_i32_e32 vcc, v107, v108
	v_mfma_f32_16x16x32_bf16 v[90:93], v[186:189], v[144:147], v[90:93]
	v_and_b32_e32 v146, 0xffff0000, v46
	v_cndmask_b32_e32 v107, v235, v107, vcc
	v_lshlrev_b32_e32 v107, 2, v107
	ds_bpermute_b32 v107, v107, v106
	v_and_b32_e32 v147, 0xffff0000, v47
	v_lshl_add_u64 v[144:145], v[134:135], 0, s[6:7]
	s_waitcnt lgkmcnt(0)
	v_add_f32_e32 v106, v106, v107
	v_xor_b32_e32 v107, 2, v235
	v_cmp_lt_i32_e32 vcc, v107, v108
	s_nop 1
	v_cndmask_b32_e32 v107, v235, v107, vcc
	v_lshlrev_b32_e32 v107, 2, v107
	ds_bpermute_b32 v107, v107, v106
	s_waitcnt lgkmcnt(0)
	v_add_f32_e32 v106, v106, v107
	v_xor_b32_e32 v107, 4, v235
	v_cmp_lt_i32_e32 vcc, v107, v108
	s_nop 1
	v_cndmask_b32_e32 v107, v235, v107, vcc
	v_lshlrev_b32_e32 v107, 2, v107
	ds_bpermute_b32 v107, v107, v106
	s_waitcnt lgkmcnt(0)
	v_add_f32_e32 v106, v106, v107
	v_fmamk_f32 v106, v106, 0x3c000000, v1
	v_cmp_gt_f32_e32 vcc, s0, v106
	v_mul_f32_e32 v107, 0x4b800000, v106
	s_nop 0
	v_cndmask_b32_e32 v106, v106, v107, vcc
	v_rsq_f32_e32 v106, v106
	s_nop 0
	v_mul_f32_e32 v107, 0x45800000, v106
	v_cndmask_b32_e32 v142, v106, v107, vcc
	v_mul_f32_e32 v106, 0xbfb8aa3b, v150
	v_exp_f32_e32 v106, v106
	v_mov_b32_e32 v107, v112
	v_mov_b32_e32 v112, v111
	v_add_f32_e32 v106, 1.0, v106
	v_rcp_f32_e32 v152, v106
	v_mul_f32_e32 v106, 0xbfb8aa3b, v146
	v_exp_f32_e32 v106, v106
	s_nop 0
	v_add_f32_e32 v106, 1.0, v106
	v_rcp_f32_e32 v148, v106
	v_mov_b32_e32 v106, v110
	v_pk_mul_f32 v[154:155], v[106:107], v[142:143] op_sel_hi:[1,0]
	v_mov_b32_e32 v106, v246
	v_mov_b32_e32 v107, v247
	v_mov_b32_e32 v108, v248
	v_mov_b32_e32 v109, v249
	v_mov_b32_e32 v114, v242
	v_mov_b32_e32 v115, v243
	v_mov_b32_e32 v116, v244
	v_mov_b32_e32 v117, v245
	v_mul_f32_e32 v110, 0xbfb8aa3b, v151
	v_exp_f32_e32 v110, v110
	v_mov_b32_e32 v171, v116
	v_add_f32_e32 v110, 1.0, v110
	v_rcp_f32_e32 v153, v110
	v_pk_mul_f32 v[110:111], v[112:113], v[142:143] op_sel_hi:[1,0]
	v_mul_f32_e32 v112, 0xbfb8aa3b, v147
	v_exp_f32_e32 v112, v112
	v_mov_b32_e32 v116, v115
	v_pk_mul_f32 v[110:111], v[116:117], v[110:111]
	v_mov_b32_e32 v170, v114
	v_add_f32_e32 v112, 1.0, v112
	v_rcp_f32_e32 v149, v112
	v_and_b32_e32 v114, 0xffff0000, v48
	v_mul_f32_e32 v117, 0xbfb8aa3b, v114
	v_exp_f32_e32 v117, v117
	v_pk_mul_f32 v[112:113], v[148:149], v[146:147]
	v_mov_b32_e32 v148, v102
	v_pk_mul_f32 v[110:111], v[112:113], v[110:111]
	v_lshlrev_b32_e32 v113, 16, v49
	v_mul_f32_e32 v102, 0xbfb8aa3b, v113
	v_exp_f32_e32 v102, v102
	v_and_b32_e32 v115, 0xffff0000, v49
	v_add_f32_e32 v117, 1.0, v117
	v_mov_b32_e32 v149, v104
	v_add_f32_e32 v102, 1.0, v102
	v_mov_b32_e32 v104, v103
	v_lshlrev_b32_e32 v112, 16, v48
	v_rcp_f32_e32 v146, v117
	v_rcp_f32_e32 v117, v102
	v_pk_mul_f32 v[102:103], v[104:105], v[142:143] op_sel_hi:[1,0]
	v_mul_f32_e32 v104, 0xbfb8aa3b, v115
	v_mul_f32_e32 v116, 0xbfb8aa3b, v112
	v_exp_f32_e32 v104, v104
	v_exp_f32_e32 v116, v116
	v_pk_mul_f32 v[150:151], v[152:153], v[150:151]
	v_mov_b32_e32 v153, v108
	v_add_f32_e32 v104, 1.0, v104
	v_add_f32_e32 v116, 1.0, v116
	v_rcp_f32_e32 v147, v104
	v_rcp_f32_e32 v116, v116
	v_mov_b32_e32 v108, v107
	v_pk_mul_f32 v[148:149], v[148:149], v[142:143] op_sel_hi:[1,0]
	v_mov_b32_e32 v152, v106
	v_pk_mul_f32 v[102:103], v[108:109], v[102:103]
	v_pk_mul_f32 v[104:105], v[146:147], v[114:115]
	v_pk_mul_f32 v[154:155], v[170:171], v[154:155]
	v_pk_mul_f32 v[148:149], v[152:153], v[148:149]
	v_pk_mul_f32 v[112:113], v[116:117], v[112:113]
	v_pk_mul_f32 v[102:103], v[104:105], v[102:103]
	v_pk_mul_f32 v[150:151], v[150:151], v[154:155]
	v_pk_mul_f32 v[112:113], v[112:113], v[148:149]
	v_bfe_u32 v105, v102, 16, 1
	v_bfe_u32 v104, v103, 16, 1
	v_add3_u32 v102, v102, v105, s33
	v_bfe_u32 v105, v151, 16, 1
	v_bfe_u32 v109, v113, 16, 1
	v_bfe_u32 v106, v111, 16, 1
	v_add3_u32 v103, v103, v104, s33
	v_bfe_u32 v104, v150, 16, 1
	v_bfe_u32 v108, v112, 16, 1
	v_add3_u32 v109, v113, v109, s33
	v_add3_u32 v105, v151, v105, s33
	v_bfe_u32 v107, v110, 16, 1
	v_add3_u32 v106, v111, v106, s33
	v_add3_u32 v108, v112, v108, s33
	v_add3_u32 v104, v150, v104, s33
	v_lshrrev_b32_e32 v111, 16, v105
	v_lshrrev_b32_e32 v105, 16, v109
	v_add3_u32 v107, v110, v107, s33
	v_lshrrev_b32_e32 v110, 16, v104
	v_lshrrev_b32_e32 v104, 16, v108
	v_and_or_b32 v105, v103, s21, v105
	v_and_or_b32 v103, v106, s21, v111
	v_add_co_u32_e32 v106, vcc, s30, v144
	v_and_or_b32 v104, v102, s21, v104
	v_and_or_b32 v102, v107, s21, v110
	v_addc_co_u32_e32 v107, vcc, 0, v145, vcc
	v_lshlrev_b32_e32 v114, 16, v50
	global_store_dwordx4 v[106:107], v[102:105], off offset:1024
	v_and_b32_e32 v108, 0xffff0000, v50
	v_lshlrev_b32_e32 v115, 16, v51
	v_mul_f32_e32 v102, 0xbfb8aa3b, v114
	v_exp_f32_e32 v102, v102
	v_mov_b32_e32 v103, v100
	v_and_b32_e32 v109, 0xffff0000, v51
	v_mov_b32_e32 v100, v99
	v_add_f32_e32 v102, 1.0, v102
	v_rcp_f32_e32 v116, v102
	v_mul_f32_e32 v102, 0xbfb8aa3b, v108
	v_exp_f32_e32 v102, v102
	s_andn2_b64 vcc, exec, s[8:9]
	v_add_f32_e32 v102, 1.0, v102
	v_rcp_f32_e32 v144, v102
	v_mov_b32_e32 v102, v98
	v_pk_mul_f32 v[146:147], v[102:103], v[142:143] op_sel_hi:[1,0]
	v_mov_b32_e32 v102, v230
	v_mov_b32_e32 v103, v234
	v_mov_b32_e32 v104, v236
	v_mov_b32_e32 v105, v238
	v_mov_b32_e32 v110, v250
	v_mov_b32_e32 v111, v251
	v_mov_b32_e32 v112, v241
	v_mov_b32_e32 v113, v228
	v_mul_f32_e32 v98, 0xbfb8aa3b, v115
	v_exp_f32_e32 v98, v98
	v_mov_b32_e32 v149, v112
	v_add_f32_e32 v98, 1.0, v98
	v_rcp_f32_e32 v117, v98
	v_pk_mul_f32 v[98:99], v[100:101], v[142:143] op_sel_hi:[1,0]
	v_mul_f32_e32 v100, 0xbfb8aa3b, v109
	v_exp_f32_e32 v100, v100
	v_mov_b32_e32 v112, v111
	v_pk_mul_f32 v[98:99], v[112:113], v[98:99]
	v_pk_mul_f32 v[114:115], v[116:117], v[114:115]
	v_add_f32_e32 v100, 1.0, v100
	v_rcp_f32_e32 v145, v100
	v_mov_b32_e32 v116, v94
	v_mov_b32_e32 v117, v96
	v_mov_b32_e32 v96, v95
	v_pk_mul_f32 v[100:101], v[144:145], v[108:109]
	v_and_b32_e32 v108, 0xffff0000, v52
	v_pk_mul_f32 v[98:99], v[100:101], v[98:99]
	v_lshlrev_b32_e32 v101, 16, v53
	v_mul_f32_e32 v111, 0xbfb8aa3b, v108
	v_mul_f32_e32 v94, 0xbfb8aa3b, v101
	v_exp_f32_e32 v111, v111
	v_exp_f32_e32 v94, v94
	v_and_b32_e32 v109, 0xffff0000, v53
	v_lshlrev_b32_e32 v100, 16, v52
	v_add_f32_e32 v111, 1.0, v111
	v_add_f32_e32 v94, 1.0, v94
	v_rcp_f32_e32 v112, v111
	v_rcp_f32_e32 v111, v94
	v_pk_mul_f32 v[94:95], v[96:97], v[142:143] op_sel_hi:[1,0]
	v_mul_f32_e32 v96, 0xbfb8aa3b, v109
	v_mov_b32_e32 v148, v110
	v_mul_f32_e32 v110, 0xbfb8aa3b, v100
	v_exp_f32_e32 v96, v96
	v_exp_f32_e32 v110, v110
	v_mov_b32_e32 v145, v104
	v_mov_b32_e32 v104, v103
	v_add_f32_e32 v96, 1.0, v96
	v_add_f32_e32 v110, 1.0, v110
	v_rcp_f32_e32 v113, v96
	v_rcp_f32_e32 v110, v110
	v_pk_mul_f32 v[116:117], v[116:117], v[142:143] op_sel_hi:[1,0]
	v_mov_b32_e32 v144, v102
	v_pk_mul_f32 v[94:95], v[94:95], v[104:105]
	v_pk_mul_f32 v[96:97], v[112:113], v[108:109]
	v_pk_mul_f32 v[146:147], v[148:149], v[146:147]
	v_pk_mul_f32 v[116:117], v[116:117], v[144:145]
	v_pk_mul_f32 v[100:101], v[110:111], v[100:101]
	v_pk_mul_f32 v[94:95], v[96:97], v[94:95]
	v_pk_mul_f32 v[114:115], v[114:115], v[146:147]
	v_pk_mul_f32 v[100:101], v[100:101], v[116:117]
	v_bfe_u32 v96, v95, 16, 1
	v_bfe_u32 v97, v94, 16, 1
	v_bfe_u32 v102, v99, 16, 1
	v_bfe_u32 v103, v98, 16, 1
	v_add3_u32 v98, v98, v103, s33
	v_add3_u32 v99, v99, v102, s33
	v_add3_u32 v94, v94, v97, s33
	v_add3_u32 v95, v95, v96, s33
	v_bfe_u32 v96, v114, 16, 1
	v_bfe_u32 v97, v115, 16, 1
	v_bfe_u32 v102, v100, 16, 1
	v_bfe_u32 v103, v101, 16, 1
	v_add3_u32 v101, v101, v103, s33
	v_add3_u32 v100, v100, v102, s33
	v_add3_u32 v97, v115, v97, s33
	v_add3_u32 v96, v114, v96, s33
	v_lshrrev_b32_e32 v102, 16, v96
	v_lshrrev_b32_e32 v103, 16, v97
	v_lshrrev_b32_e32 v96, 16, v100
	v_lshrrev_b32_e32 v97, 16, v101
	v_and_or_b32 v97, v95, s21, v97
	v_and_or_b32 v96, v94, s21, v96
	v_and_or_b32 v95, v99, s21, v103
	v_and_or_b32 v94, v98, s21, v102
	global_store_dwordx4 v[106:107], v[94:97], off offset:1040
	s_cbranch_vccnz .LBB0_444
	s_waitcnt vmcnt(2)
	v_mov_b64_e32 v[46:47], v[58:59]
	v_mov_b64_e32 v[50:51], v[54:55]
	v_mov_b64_e32 v[48:49], v[60:61]
	v_mov_b64_e32 v[52:53], v[56:57]
	v_mov_b32_e32 v130, v162
	ds_write_b128 v119, v[2:5]
	ds_write_b128 v156, v[6:9]
	ds_write_b128 v119, v[10:13] offset:17408
	ds_write_b128 v156, v[14:17] offset:17408
	ds_write_b128 v143, v[18:21] offset:34816
	ds_write_b128 v143, v[22:25] offset:44032
	ds_write_b128 v157, v[26:29] offset:44032
	ds_write_b128 v158, v[30:33]
	ds_write_b128 v159, v[34:37]
	ds_write_b128 v160, v[38:41]
	ds_write_b128 v161, v[42:45]
	s_branch .LBB0_444
